# flips deleted plus ONE static s_setprio 1 for waves 4-7 at kernel entry (docs 7.4 recipe)
# baseline (speedup 1.0000x reference)
; __device__ __forceinline__ int lane_fresh() { int l; asm volatile("v_mbcnt_lo_u32_b32 %0, -1, 0\n\tv_mbcnt_hi_u32_b32 %0, -1, %0" : "=v"(l)); return l; }
; __device__ __forceinline__ unsigned xb_add(unsigned* p, unsigned v) { return __hip_atomic_fetch_add(p, v, __ATOMIC_RELAXED, __HIP_MEMORY_SCOPE_AGENT); }
; __device__ __forceinline__ unsigned xb_xcc_id() { return (unsigned)__builtin_amdgcn_s_getreg((3 << 11) | 20) & 0xFu; }
; __global__ void __launch_bounds__(NTHREADS) fwd_megakernel(Params p) {
;   cg::grid_group grid = cg::this_grid();
;   const int wv = __builtin_amdgcn_readfirstlane(threadIdx.x >> 6);
;     ...
;   unsigned* bar = (unsigned*)(p.ws + OFF_BAR);
;   if (wv == 0) { if (lane_fresh() == 0) { xb_words = make_uint4(0u, 0u, 0u, 0u); (void)xb_add(&bar[XB_XCNT(xb_xcc_id())], 1u); } }
_Z14fwd_megakernel6Params:
	v_readfirstlane_b32 s100, v0
	s_nop 3
	s_bfe_u32 s100, s100, 0x40006
	s_cmp_ge_u32 s100, 4
	s_cbranch_scc0 .Lprio_k
	s_setprio 1
.Lprio_k:
	s_load_dwordx16 s[56:71], s[0:1], 0x40
	s_load_dwordx16 s[36:51], s[0:1], 0xc0
	v_writelane_b32 v251, s2, 0
	s_load_dword s2, s[0:1], 0x100
	s_add_u32 s6, s0, 0x100
	s_addc_u32 s7, s1, 0
	v_and_b32_e32 v1, 0x3ff, v0
	s_waitcnt lgkmcnt(0)
	v_writelane_b32 v251, s2, 1
	s_add_u32 s2, s50, 0x12416000
	v_readfirstlane_b32 s81, v1
	s_addc_u32 s3, s51, 0
	s_cmp_lt_u32 s81, 64
	v_writelane_b32 v251, s2, 2
	s_cselect_b64 s[4:5], -1, 0
	s_cmp_gt_u32 s81, 63
	v_writelane_b32 v251, s3, 3
	s_cselect_b64 s[2:3], -1, 0
	v_writelane_b32 v251, s2, 4
	s_and_b64 vcc, exec, s[2:3]
	s_nop 0
	v_writelane_b32 v251, s3, 5
	s_cbranch_vccnz .LBB0_5
	v_mbcnt_lo_u32_b32 v2, -1, 0
	v_mbcnt_hi_u32_b32 v2, -1, v2
	s_nop 0
	v_cmp_eq_u32_e32 vcc, 0, v2
	s_and_saveexec_b64 s[2:3], vcc
	s_cbranch_execz .LBB0_4
	v_mov_b32_e32 v2, 0
	s_mov_b64 s[8:9], exec
	v_mov_b32_e32 v3, v2
	v_mov_b32_e32 v4, v2
	v_mov_b32_e32 v5, v2
	ds_write_b128 v2, v[2:5]
	v_mbcnt_lo_u32_b32 v2, s8, 0
	v_mbcnt_hi_u32_b32 v2, s9, v2
	v_cmp_eq_u32_e32 vcc, 0, v2
	s_getreg_b32 s10, hwreg(HW_REG_XCC_ID, 0, 4)
	s_and_b64 s[12:13], exec, vcc
	s_mov_b64 exec, s[12:13]
	s_cbranch_execz .LBB0_4
	s_lshl_b32 s10, s10, 8
	s_bcnt1_i32_b64 s8, s[8:9]
	s_and_b32 s10, s10, 0xf00
	v_mov_b32_e32 v3, s8
	v_readlane_b32 s8, v251, 2
	v_mov_b32_e32 v2, s10
	v_readlane_b32 s9, v251, 3
	s_nop 4
	global_atomic_add v2, v3, s[8:9] offset:1024
